# P2/P5 GEMM epilogues: bf16 row stores widened to dwordx4 via v_permlane16_swap (counted waits re-derived)
# speedup vs baseline: 1.0272x; 1.0075x over previous
.LBB0_263:
	v_mbcnt_lo_u32_b32 v242, -1, 0
	v_mbcnt_hi_u32_b32 v242, -1, v242
	v_bfe_u32 v242, v242, 4, 1
	v_mul_u32_u24_e32 v242, 24, v242
	v_mov_b32_e32 v243, 0
	v_lshl_or_b32 v140, s77, 8, v180
	v_lshl_add_u32 v184, s76, 8, v176
	v_ashrrev_i32_e32 v141, 31, v140
	v_lshlrev_b64 v[186:187], 1, v[140:141]
	v_ashrrev_i32_e32 v185, 31, v184
	v_lshl_add_u64 v[142:143], s[34:35], 0, v[186:187]
	v_lshlrev_b64 v[144:145], 12, v[184:185]
	v_lshl_add_u64 v[146:147], v[142:143], 0, v[144:145]
	global_load_dwordx2 v[188:189], v[146:147], off
	global_load_dwordx2 v[190:191], v[146:147], off offset:32
	global_load_dwordx2 v[192:193], v[146:147], off offset:256
	global_load_dwordx2 v[194:195], v[146:147], off offset:288
	v_or_b32_e32 v146, 16, v184
	v_or_b32_e32 v148, 32, v184
	v_or_b32_e32 v150, 48, v184
	v_ashrrev_i32_e32 v147, 31, v146
	v_ashrrev_i32_e32 v149, 31, v148
	v_ashrrev_i32_e32 v151, 31, v150
	v_lshlrev_b64 v[166:167], 12, v[146:147]
	v_lshlrev_b64 v[156:157], 12, v[148:149]
	v_lshlrev_b64 v[146:147], 12, v[150:151]
	v_lshl_add_u64 v[148:149], v[142:143], 0, v[166:167]
	v_lshl_add_u64 v[150:151], v[142:143], 0, v[156:157]
	v_lshl_add_u64 v[196:197], v[142:143], 0, v[146:147]
	global_load_dwordx2 v[174:175], v[148:149], off
	global_load_dwordx2 v[172:173], v[148:149], off offset:32
	global_load_dwordx2 v[170:171], v[148:149], off offset:256
	global_load_dwordx2 v[168:169], v[148:149], off offset:288
	global_load_dwordx2 v[164:165], v[150:151], off
	global_load_dwordx2 v[162:163], v[150:151], off offset:32
	global_load_dwordx2 v[160:161], v[150:151], off offset:256
	global_load_dwordx2 v[158:159], v[150:151], off offset:288
	global_load_dwordx2 v[154:155], v[196:197], off
	global_load_dwordx2 v[152:153], v[196:197], off offset:32
	s_nop 0
	global_load_dwordx2 v[150:151], v[196:197], off offset:256
	global_load_dwordx2 v[148:149], v[196:197], off offset:288
	v_lshl_add_u64 v[196:197], s[34:35], 0, v[144:145]
	v_lshl_add_u64 v[186:187], v[196:197], 0, v[186:187]
	s_waitcnt vmcnt(0)
	v_lshlrev_b32_e32 v196, 16, v188
	v_and_b32_e32 v197, 0xffff0000, v188
	v_lshlrev_b32_e32 v188, 16, v189
	v_and_b32_e32 v189, 0xffff0000, v189
	v_lshlrev_b32_e32 v198, 16, v190
	v_and_b32_e32 v199, 0xffff0000, v190
	v_lshlrev_b32_e32 v190, 16, v191
	v_and_b32_e32 v191, 0xffff0000, v191
	v_lshlrev_b32_e32 v200, 16, v192
	v_and_b32_e32 v201, 0xffff0000, v192
	v_lshlrev_b32_e32 v192, 16, v193
	v_and_b32_e32 v193, 0xffff0000, v193
	v_lshlrev_b32_e32 v202, 16, v194
	v_and_b32_e32 v203, 0xffff0000, v194
	v_lshlrev_b32_e32 v194, 16, v195
	v_and_b32_e32 v195, 0xffff0000, v195
	v_pk_fma_f32 v[126:127], v[126:127], 0.5, v[188:189] op_sel_hi:[1,0,1]
	v_pk_fma_f32 v[124:125], v[124:125], 0.5, v[196:197] op_sel_hi:[1,0,1]
	v_pk_fma_f32 v[122:123], v[122:123], 0.5, v[190:191] op_sel_hi:[1,0,1]
	v_pk_fma_f32 v[120:121], v[120:121], 0.5, v[198:199] op_sel_hi:[1,0,1]
	v_pk_fma_f32 v[118:119], v[118:119], 0.5, v[192:193] op_sel_hi:[1,0,1]
	v_pk_fma_f32 v[116:117], v[116:117], 0.5, v[200:201] op_sel_hi:[1,0,1]
	v_pk_fma_f32 v[188:189], v[114:115], 0.5, v[194:195] op_sel_hi:[1,0,1]
	v_mul_f32_e32 v190, v125, v125
	v_mul_f32_e32 v191, v127, v127
	v_cvt_pk_bf16_f32 v232, v124, v125
	v_cvt_pk_bf16_f32 v233, v126, v127
	v_mul_f32_e32 v125, v121, v121
	v_mul_f32_e32 v127, v123, v123
	v_pk_fma_f32 v[112:113], v[112:113], 0.5, v[202:203] op_sel_hi:[1,0,1]
	v_mul_f32_e32 v192, v117, v117
	v_mul_f32_e32 v193, v119, v119
	v_fmac_f32_e32 v190, v124, v124
	v_fmac_f32_e32 v191, v126, v126
	v_fmac_f32_e32 v125, v120, v120
	v_fmac_f32_e32 v127, v122, v122
	v_mul_f32_e32 v194, v113, v113
	v_mul_f32_e32 v195, v189, v189
	v_cvt_pk_bf16_f32 v234, v120, v121
	v_fmac_f32_e32 v192, v116, v116
	v_fmac_f32_e32 v193, v118, v118
	v_add_f32_e32 v120, v190, v191
	v_add_f32_e32 v121, v125, v127
	v_cvt_pk_bf16_f32 v235, v122, v123
	v_fmac_f32_e32 v194, v112, v112
	v_fmac_f32_e32 v195, v188, v188
	v_add_f32_e32 v122, v192, v193
	v_add_f32_e32 v120, v120, v121
	v_add_f32_e32 v120, v120, v122
	v_add_f32_e32 v121, v194, v195
	v_add_f32_e32 v120, v120, v121
	ds_bpermute_b32 v121, v178, v120
	s_nop 1
	v_permlane16_swap_b32 v232, v234
	v_permlane16_swap_b32 v233, v235
	v_lshl_add_u64 v[240:241], v[186:187], 0, v[242:243]
	global_store_dwordx4 v[240:241], v[232:235], off
	v_cvt_pk_bf16_f32 v236, v116, v117
	v_cvt_pk_bf16_f32 v237, v118, v119
	s_waitcnt lgkmcnt(0)
	v_add_f32_e32 v114, v120, v121
	ds_bpermute_b32 v115, v179, v114
	v_cvt_pk_bf16_f32 v238, v112, v113
	v_cvt_pk_bf16_f32 v239, v188, v189
	s_nop 1
	v_permlane16_swap_b32 v236, v238
	v_permlane16_swap_b32 v237, v239
	v_lshl_add_u64 v[240:241], v[186:187], 0, v[242:243]
	global_store_dwordx4 v[240:241], v[236:239], off offset:256
	v_lshl_add_u64 v[112:113], v[184:185], 2, s[26:27]
	s_and_saveexec_b64 s[50:51], s[6:7]
	s_cbranch_execz .LBB0_265
	s_waitcnt lgkmcnt(0)
	v_add_f32_e32 v114, v114, v115
	global_atomic_add_f32 v[112:113], v114, off
.LBB0_265:
	s_or_b64 exec, exec, s[50:51]
	v_lshlrev_b32_e32 v114, 16, v174
	s_waitcnt lgkmcnt(0)
	v_and_b32_e32 v115, 0xffff0000, v174
	v_lshlrev_b32_e32 v116, 16, v175
	v_and_b32_e32 v117, 0xffff0000, v175
	v_pk_fma_f32 v[110:111], v[110:111], 0.5, v[116:117] op_sel_hi:[1,0,1]
	v_pk_fma_f32 v[108:109], v[108:109], 0.5, v[114:115] op_sel_hi:[1,0,1]
	v_mul_f32_e32 v115, v111, v111
	v_mul_f32_e32 v114, v109, v109
	v_lshlrev_b32_e32 v118, 16, v172
	v_and_b32_e32 v119, 0xffff0000, v172
	v_lshlrev_b32_e32 v120, 16, v173
	v_and_b32_e32 v121, 0xffff0000, v173
	v_fmac_f32_e32 v114, v108, v108
	v_fmac_f32_e32 v115, v110, v110
	v_cvt_pk_bf16_f32 v232, v108, v109
	v_cvt_pk_bf16_f32 v233, v110, v111
	v_lshl_add_u64 v[110:111], s[34:35], 0, v[166:167]
	v_lshl_add_u64 v[110:111], v[140:141], 1, v[110:111]
	v_pk_fma_f32 v[106:107], v[106:107], 0.5, v[120:121] op_sel_hi:[1,0,1]
	v_pk_fma_f32 v[104:105], v[104:105], 0.5, v[118:119] op_sel_hi:[1,0,1]
	v_lshlrev_b32_e32 v122, 16, v170
	v_and_b32_e32 v123, 0xffff0000, v170
	v_lshlrev_b32_e32 v124, 16, v171
	v_and_b32_e32 v125, 0xffff0000, v171
	v_mul_f32_e32 v108, v105, v105
	v_mul_f32_e32 v109, v107, v107
	v_fmac_f32_e32 v108, v104, v104
	v_fmac_f32_e32 v109, v106, v106
	v_pk_fma_f32 v[102:103], v[102:103], 0.5, v[124:125] op_sel_hi:[1,0,1]
	v_pk_fma_f32 v[100:101], v[100:101], 0.5, v[122:123] op_sel_hi:[1,0,1]
	v_add_f32_e32 v108, v108, v109
	v_cvt_pk_bf16_f32 v234, v104, v105
	v_mul_f32_e32 v105, v101, v101
	v_mul_f32_e32 v109, v103, v103
	v_add_f32_e32 v114, v114, v115
	v_fmac_f32_e32 v105, v100, v100
	v_fmac_f32_e32 v109, v102, v102
	v_lshlrev_b32_e32 v126, 16, v168
	v_and_b32_e32 v127, 0xffff0000, v168
	v_lshlrev_b32_e32 v168, 16, v169
	v_and_b32_e32 v169, 0xffff0000, v169
	v_add_f32_e32 v108, v114, v108
	v_add_f32_e32 v105, v105, v109
	v_add_f32_e32 v105, v108, v105
	v_pk_fma_f32 v[98:99], v[98:99], 0.5, v[168:169] op_sel_hi:[1,0,1]
	v_pk_fma_f32 v[108:109], v[96:97], 0.5, v[126:127] op_sel_hi:[1,0,1]
	v_mul_f32_e32 v97, v99, v99
	v_mul_f32_e32 v96, v109, v109
	v_fmac_f32_e32 v96, v108, v108
	v_fmac_f32_e32 v97, v98, v98
	v_add_f32_e32 v96, v96, v97
	v_add_f32_e32 v96, v105, v96
	ds_bpermute_b32 v97, v178, v96
	v_cvt_pk_bf16_f32 v235, v106, v107
	s_nop 1
	v_permlane16_swap_b32 v232, v234
	v_permlane16_swap_b32 v233, v235
	v_lshl_add_u64 v[240:241], v[110:111], 0, v[242:243]
	global_store_dwordx4 v[240:241], v[232:235], off
	v_cvt_pk_bf16_f32 v236, v100, v101
	v_cvt_pk_bf16_f32 v237, v102, v103
	s_waitcnt lgkmcnt(0)
	v_add_f32_e32 v96, v96, v97
	ds_bpermute_b32 v97, v179, v96
	v_cvt_pk_bf16_f32 v238, v108, v109
	v_cvt_pk_bf16_f32 v239, v98, v99
	s_nop 1
	v_permlane16_swap_b32 v236, v238
	v_permlane16_swap_b32 v237, v239
	v_lshl_add_u64 v[240:241], v[110:111], 0, v[242:243]
	global_store_dwordx4 v[240:241], v[236:239], off offset:256
	s_and_saveexec_b64 s[50:51], s[6:7]
	s_cbranch_execz .LBB0_267
	s_waitcnt lgkmcnt(0)
	v_add_f32_e32 v96, v96, v97
	global_atomic_add_f32 v[112:113], v96, off offset:64
.LBB0_267:
	s_or_b64 exec, exec, s[50:51]
	v_lshlrev_b32_e32 v96, 16, v164
	s_waitcnt lgkmcnt(0)
	v_and_b32_e32 v97, 0xffff0000, v164
	v_lshlrev_b32_e32 v98, 16, v165
	v_and_b32_e32 v99, 0xffff0000, v165
	v_pk_fma_f32 v[94:95], v[94:95], 0.5, v[98:99] op_sel_hi:[1,0,1]
	v_pk_fma_f32 v[92:93], v[92:93], 0.5, v[96:97] op_sel_hi:[1,0,1]
	v_mul_f32_e32 v97, v95, v95
	v_mul_f32_e32 v96, v93, v93
	v_lshlrev_b32_e32 v100, 16, v162
	v_and_b32_e32 v101, 0xffff0000, v162
	v_lshlrev_b32_e32 v102, 16, v163
	v_and_b32_e32 v103, 0xffff0000, v163
	v_fmac_f32_e32 v96, v92, v92
	v_fmac_f32_e32 v97, v94, v94
	v_cvt_pk_bf16_f32 v232, v92, v93
	v_cvt_pk_bf16_f32 v233, v94, v95
	v_lshl_add_u64 v[94:95], s[34:35], 0, v[156:157]
	v_lshl_add_u64 v[94:95], v[140:141], 1, v[94:95]
	v_pk_fma_f32 v[90:91], v[90:91], 0.5, v[102:103] op_sel_hi:[1,0,1]
	v_pk_fma_f32 v[88:89], v[88:89], 0.5, v[100:101] op_sel_hi:[1,0,1]
	v_lshlrev_b32_e32 v104, 16, v160
	v_and_b32_e32 v105, 0xffff0000, v160
	v_lshlrev_b32_e32 v106, 16, v161
	v_and_b32_e32 v107, 0xffff0000, v161
	v_mul_f32_e32 v92, v89, v89
	v_mul_f32_e32 v93, v91, v91
	v_fmac_f32_e32 v92, v88, v88
	v_fmac_f32_e32 v93, v90, v90
	v_pk_fma_f32 v[86:87], v[86:87], 0.5, v[106:107] op_sel_hi:[1,0,1]
	v_pk_fma_f32 v[84:85], v[84:85], 0.5, v[104:105] op_sel_hi:[1,0,1]
	v_add_f32_e32 v92, v92, v93
	v_cvt_pk_bf16_f32 v234, v88, v89
	v_mul_f32_e32 v89, v85, v85
	v_mul_f32_e32 v93, v87, v87
	v_add_f32_e32 v96, v96, v97
	v_fmac_f32_e32 v89, v84, v84
	v_fmac_f32_e32 v93, v86, v86
	v_lshlrev_b32_e32 v108, 16, v158
	v_and_b32_e32 v109, 0xffff0000, v158
	v_lshlrev_b32_e32 v110, 16, v159
	v_and_b32_e32 v111, 0xffff0000, v159
	v_add_f32_e32 v92, v96, v92
	v_add_f32_e32 v89, v89, v93
	v_add_f32_e32 v89, v92, v89
	v_pk_fma_f32 v[82:83], v[82:83], 0.5, v[110:111] op_sel_hi:[1,0,1]
	v_pk_fma_f32 v[92:93], v[80:81], 0.5, v[108:109] op_sel_hi:[1,0,1]
	v_mul_f32_e32 v81, v83, v83
	v_mul_f32_e32 v80, v93, v93
	v_fmac_f32_e32 v80, v92, v92
	v_fmac_f32_e32 v81, v82, v82
	v_add_f32_e32 v80, v80, v81
	v_add_f32_e32 v80, v89, v80
	ds_bpermute_b32 v81, v178, v80
	v_cvt_pk_bf16_f32 v235, v90, v91
	s_nop 1
	v_permlane16_swap_b32 v232, v234
	v_permlane16_swap_b32 v233, v235
	v_lshl_add_u64 v[240:241], v[94:95], 0, v[242:243]
	global_store_dwordx4 v[240:241], v[232:235], off
	v_cvt_pk_bf16_f32 v236, v84, v85
	v_cvt_pk_bf16_f32 v237, v86, v87
	s_waitcnt lgkmcnt(0)
	v_add_f32_e32 v80, v80, v81
	ds_bpermute_b32 v81, v179, v80
	v_cvt_pk_bf16_f32 v238, v92, v93
	v_cvt_pk_bf16_f32 v239, v82, v83
	s_nop 1
	v_permlane16_swap_b32 v236, v238
	v_permlane16_swap_b32 v237, v239
	v_lshl_add_u64 v[240:241], v[94:95], 0, v[242:243]
	global_store_dwordx4 v[240:241], v[236:239], off offset:256
	s_and_saveexec_b64 s[50:51], s[6:7]
	s_cbranch_execz .LBB0_269
	s_waitcnt lgkmcnt(0)
	v_add_f32_e32 v80, v80, v81
	global_atomic_add_f32 v[112:113], v80, off offset:128
.LBB0_269:
	s_or_b64 exec, exec, s[50:51]
	v_lshlrev_b32_e32 v80, 16, v154
	s_waitcnt lgkmcnt(0)
	v_and_b32_e32 v81, 0xffff0000, v154
	v_lshlrev_b32_e32 v82, 16, v155
	v_and_b32_e32 v83, 0xffff0000, v155
	v_pk_fma_f32 v[78:79], v[78:79], 0.5, v[82:83] op_sel_hi:[1,0,1]
	v_pk_fma_f32 v[76:77], v[76:77], 0.5, v[80:81] op_sel_hi:[1,0,1]
	v_mul_f32_e32 v81, v79, v79
	v_mul_f32_e32 v80, v77, v77
	v_lshlrev_b32_e32 v84, 16, v152
	v_and_b32_e32 v85, 0xffff0000, v152
	v_lshlrev_b32_e32 v86, 16, v153
	v_and_b32_e32 v87, 0xffff0000, v153
	v_fmac_f32_e32 v80, v76, v76
	v_fmac_f32_e32 v81, v78, v78
	v_cvt_pk_bf16_f32 v232, v76, v77
	v_cvt_pk_bf16_f32 v233, v78, v79
	v_lshl_add_u64 v[78:79], s[34:35], 0, v[146:147]
	v_lshl_add_u64 v[78:79], v[140:141], 1, v[78:79]
	v_pk_fma_f32 v[74:75], v[74:75], 0.5, v[86:87] op_sel_hi:[1,0,1]
	v_pk_fma_f32 v[72:73], v[72:73], 0.5, v[84:85] op_sel_hi:[1,0,1]
	v_lshlrev_b32_e32 v88, 16, v150
	v_and_b32_e32 v89, 0xffff0000, v150
	v_lshlrev_b32_e32 v90, 16, v151
	v_and_b32_e32 v91, 0xffff0000, v151
	v_mul_f32_e32 v76, v73, v73
	v_mul_f32_e32 v77, v75, v75
	v_fmac_f32_e32 v76, v72, v72
	v_fmac_f32_e32 v77, v74, v74
	v_pk_fma_f32 v[70:71], v[70:71], 0.5, v[90:91] op_sel_hi:[1,0,1]
	v_pk_fma_f32 v[68:69], v[68:69], 0.5, v[88:89] op_sel_hi:[1,0,1]
	v_add_f32_e32 v76, v76, v77
	v_cvt_pk_bf16_f32 v234, v72, v73
	v_mul_f32_e32 v73, v69, v69
	v_mul_f32_e32 v77, v71, v71
	v_add_f32_e32 v80, v80, v81
	v_fmac_f32_e32 v73, v68, v68
	v_fmac_f32_e32 v77, v70, v70
	v_lshlrev_b32_e32 v92, 16, v148
	v_and_b32_e32 v93, 0xffff0000, v148
	v_lshlrev_b32_e32 v94, 16, v149
	v_and_b32_e32 v95, 0xffff0000, v149
	v_add_f32_e32 v76, v80, v76
	v_add_f32_e32 v73, v73, v77
	v_add_f32_e32 v73, v76, v73
	v_pk_fma_f32 v[66:67], v[66:67], 0.5, v[94:95] op_sel_hi:[1,0,1]
	v_pk_fma_f32 v[76:77], v[64:65], 0.5, v[92:93] op_sel_hi:[1,0,1]
	v_mul_f32_e32 v65, v67, v67
	v_mul_f32_e32 v64, v77, v77
	v_fmac_f32_e32 v64, v76, v76
	v_fmac_f32_e32 v65, v66, v66
	v_add_f32_e32 v64, v64, v65
	v_add_f32_e32 v64, v73, v64
	ds_bpermute_b32 v65, v178, v64
	v_cvt_pk_bf16_f32 v235, v74, v75
	s_nop 1
	v_permlane16_swap_b32 v232, v234
	v_permlane16_swap_b32 v233, v235
	v_lshl_add_u64 v[240:241], v[78:79], 0, v[242:243]
	global_store_dwordx4 v[240:241], v[232:235], off
	v_cvt_pk_bf16_f32 v236, v68, v69
	v_cvt_pk_bf16_f32 v237, v70, v71
	s_waitcnt lgkmcnt(0)
	v_add_f32_e32 v64, v64, v65
	ds_bpermute_b32 v65, v179, v64
	v_cvt_pk_bf16_f32 v238, v76, v77
	v_cvt_pk_bf16_f32 v239, v66, v67
	s_nop 1
	v_permlane16_swap_b32 v236, v238
	v_permlane16_swap_b32 v237, v239
	v_lshl_add_u64 v[240:241], v[78:79], 0, v[242:243]
	global_store_dwordx4 v[240:241], v[236:239], off offset:256
	s_and_saveexec_b64 s[50:51], s[6:7]
	s_cbranch_execz .LBB0_271
	s_waitcnt lgkmcnt(0)
	v_add_f32_e32 v64, v64, v65
	global_atomic_add_f32 v[112:113], v64, off offset:192
.LBB0_271:
	s_or_b64 exec, exec, s[50:51]
	s_mov_b64 s[50:51], 0x80000
	v_lshl_add_u64 v[94:95], v[144:145], 0, s[50:51]
	s_waitcnt lgkmcnt(0)
	v_lshl_add_u64 v[64:65], v[142:143], 0, v[94:95]
	global_load_dwordx2 v[96:97], v[64:65], off
	global_load_dwordx2 v[98:99], v[64:65], off offset:32
	global_load_dwordx2 v[100:101], v[64:65], off offset:256
	global_load_dwordx2 v[102:103], v[64:65], off offset:288
	s_mov_b64 s[50:51], 0x90000
	v_lshl_add_u64 v[74:75], v[144:145], 0, s[20:21]
	v_lshl_add_u64 v[64:65], v[144:145], 0, s[46:47]
	v_lshl_add_u64 v[84:85], v[144:145], 0, s[50:51]
	v_lshl_add_u64 v[66:67], v[142:143], 0, v[74:75]
	v_lshl_add_u64 v[86:87], v[142:143], 0, v[64:65]
	v_lshl_add_u64 v[104:105], v[142:143], 0, v[84:85]
	global_load_dwordx2 v[82:83], v[66:67], off
	global_load_dwordx2 v[80:81], v[66:67], off offset:32
	global_load_dwordx2 v[78:79], v[66:67], off offset:256
	global_load_dwordx2 v[76:77], v[66:67], off offset:288
	global_load_dwordx2 v[72:73], v[86:87], off
	global_load_dwordx2 v[70:71], v[86:87], off offset:32
	global_load_dwordx2 v[68:69], v[86:87], off offset:256
	s_nop 0
	global_load_dwordx2 v[66:67], v[86:87], off offset:288
	global_load_dwordx2 v[92:93], v[104:105], off
	global_load_dwordx2 v[90:91], v[104:105], off offset:32
	global_load_dwordx2 v[88:89], v[104:105], off offset:256
	s_nop 0
	global_load_dwordx2 v[86:87], v[104:105], off offset:288
	v_lshl_add_u64 v[94:95], s[34:35], 0, v[94:95]
	v_lshl_add_u64 v[94:95], v[140:141], 1, v[94:95]
	s_waitcnt vmcnt(15)
	v_lshlrev_b32_e32 v104, 16, v96
	v_and_b32_e32 v105, 0xffff0000, v96
	v_lshlrev_b32_e32 v96, 16, v97
	v_and_b32_e32 v97, 0xffff0000, v97
	s_waitcnt vmcnt(14)
	v_lshlrev_b32_e32 v106, 16, v98
	v_and_b32_e32 v107, 0xffff0000, v98
	v_lshlrev_b32_e32 v98, 16, v99
	v_and_b32_e32 v99, 0xffff0000, v99
	s_waitcnt vmcnt(13)
	v_lshlrev_b32_e32 v108, 16, v100
	v_and_b32_e32 v109, 0xffff0000, v100
	v_lshlrev_b32_e32 v100, 16, v101
	v_and_b32_e32 v101, 0xffff0000, v101
	s_waitcnt vmcnt(12)
	v_lshlrev_b32_e32 v110, 16, v102
	v_and_b32_e32 v111, 0xffff0000, v102
	v_pk_fma_f32 v[62:63], v[62:63], 0.5, v[96:97] op_sel_hi:[1,0,1]
	v_pk_fma_f32 v[60:61], v[60:61], 0.5, v[104:105] op_sel_hi:[1,0,1]
	v_pk_fma_f32 v[58:59], v[58:59], 0.5, v[98:99] op_sel_hi:[1,0,1]
	v_pk_fma_f32 v[56:57], v[56:57], 0.5, v[106:107] op_sel_hi:[1,0,1]
	v_lshlrev_b32_e32 v102, 16, v103
	v_and_b32_e32 v103, 0xffff0000, v103
	v_pk_fma_f32 v[54:55], v[54:55], 0.5, v[100:101] op_sel_hi:[1,0,1]
	v_pk_fma_f32 v[52:53], v[52:53], 0.5, v[108:109] op_sel_hi:[1,0,1]
	v_pk_fma_f32 v[96:97], v[48:49], 0.5, v[110:111] op_sel_hi:[1,0,1]
	v_mul_f32_e32 v98, v61, v61
	v_mul_f32_e32 v99, v63, v63
	v_cvt_pk_bf16_f32 v232, v60, v61
	v_cvt_pk_bf16_f32 v233, v62, v63
	v_mul_f32_e32 v61, v57, v57
	v_mul_f32_e32 v63, v59, v59
	v_pk_fma_f32 v[50:51], v[50:51], 0.5, v[102:103] op_sel_hi:[1,0,1]
	v_mul_f32_e32 v100, v53, v53
	v_mul_f32_e32 v101, v55, v55
	v_fmac_f32_e32 v98, v60, v60
	v_fmac_f32_e32 v99, v62, v62
	v_fmac_f32_e32 v61, v56, v56
	v_fmac_f32_e32 v63, v58, v58
	v_mul_f32_e32 v102, v97, v97
	v_mul_f32_e32 v103, v51, v51
	v_cvt_pk_bf16_f32 v234, v56, v57
	v_fmac_f32_e32 v100, v52, v52
	v_fmac_f32_e32 v101, v54, v54
	v_add_f32_e32 v49, v98, v99
	v_add_f32_e32 v56, v61, v63
	v_fmac_f32_e32 v102, v96, v96
	v_fmac_f32_e32 v103, v50, v50
	v_add_f32_e32 v57, v100, v101
	v_add_f32_e32 v49, v49, v56
	v_add_f32_e32 v49, v49, v57
	v_add_f32_e32 v56, v102, v103
	v_add_f32_e32 v56, v49, v56
	ds_bpermute_b32 v57, v178, v56
	v_cvt_pk_bf16_f32 v235, v58, v59
	s_nop 1
	v_permlane16_swap_b32 v232, v234
	v_permlane16_swap_b32 v233, v235
	v_lshl_add_u64 v[240:241], v[94:95], 0, v[242:243]
	global_store_dwordx4 v[240:241], v[232:235], off
	v_cvt_pk_bf16_f32 v236, v52, v53
	v_cvt_pk_bf16_f32 v237, v54, v55
	s_waitcnt lgkmcnt(0)
	v_add_f32_e32 v48, v56, v57
	ds_bpermute_b32 v49, v179, v48
	v_cvt_pk_bf16_f32 v238, v96, v97
	v_cvt_pk_bf16_f32 v239, v50, v51
	s_nop 1
	v_permlane16_swap_b32 v236, v238
	v_permlane16_swap_b32 v237, v239
	v_lshl_add_u64 v[240:241], v[94:95], 0, v[242:243]
	global_store_dwordx4 v[240:241], v[236:239], off offset:256
	s_and_saveexec_b64 s[50:51], s[6:7]
	s_cbranch_execz .LBB0_273
	s_waitcnt lgkmcnt(0)
	v_add_f32_e32 v48, v48, v49
	global_atomic_add_f32 v[112:113], v48, off offset:512
.LBB0_273:
	s_or_b64 exec, exec, s[50:51]
	s_waitcnt vmcnt(5)
	v_lshlrev_b32_e32 v48, 16, v92
	s_waitcnt lgkmcnt(0)
	v_and_b32_e32 v49, 0xffff0000, v92
	v_lshlrev_b32_e32 v50, 16, v93
	v_and_b32_e32 v51, 0xffff0000, v93
	v_pk_fma_f32 v[46:47], v[46:47], 0.5, v[50:51] op_sel_hi:[1,0,1]
	v_pk_fma_f32 v[44:45], v[44:45], 0.5, v[48:49] op_sel_hi:[1,0,1]
	v_mul_f32_e32 v49, v47, v47
	v_mul_f32_e32 v48, v45, v45
	s_waitcnt vmcnt(4)
	v_lshlrev_b32_e32 v52, 16, v90
	v_and_b32_e32 v53, 0xffff0000, v90
	v_lshlrev_b32_e32 v54, 16, v91
	v_and_b32_e32 v55, 0xffff0000, v91
	v_fmac_f32_e32 v48, v44, v44
	v_fmac_f32_e32 v49, v46, v46
	v_cvt_pk_bf16_f32 v232, v44, v45
	v_cvt_pk_bf16_f32 v233, v46, v47
	v_lshl_add_u64 v[46:47], s[34:35], 0, v[84:85]
	v_lshl_add_u64 v[46:47], v[140:141], 1, v[46:47]
	v_pk_fma_f32 v[42:43], v[42:43], 0.5, v[54:55] op_sel_hi:[1,0,1]
	v_pk_fma_f32 v[40:41], v[40:41], 0.5, v[52:53] op_sel_hi:[1,0,1]
	s_waitcnt vmcnt(3)
	v_lshlrev_b32_e32 v56, 16, v88
	v_and_b32_e32 v57, 0xffff0000, v88
	v_lshlrev_b32_e32 v58, 16, v89
	v_and_b32_e32 v59, 0xffff0000, v89
	v_mul_f32_e32 v44, v41, v41
	v_mul_f32_e32 v45, v43, v43
	v_fmac_f32_e32 v44, v40, v40
	v_fmac_f32_e32 v45, v42, v42
	v_pk_fma_f32 v[38:39], v[38:39], 0.5, v[58:59] op_sel_hi:[1,0,1]
	v_pk_fma_f32 v[36:37], v[36:37], 0.5, v[56:57] op_sel_hi:[1,0,1]
	v_add_f32_e32 v44, v44, v45
	v_cvt_pk_bf16_f32 v234, v40, v41
	v_mul_f32_e32 v41, v37, v37
	v_mul_f32_e32 v45, v39, v39
	v_add_f32_e32 v48, v48, v49
	v_fmac_f32_e32 v41, v36, v36
	v_fmac_f32_e32 v45, v38, v38
	s_waitcnt vmcnt(2)
	v_lshlrev_b32_e32 v60, 16, v86
	v_and_b32_e32 v61, 0xffff0000, v86
	v_lshlrev_b32_e32 v62, 16, v87
	v_and_b32_e32 v63, 0xffff0000, v87
	v_add_f32_e32 v44, v48, v44
	v_add_f32_e32 v41, v41, v45
	v_add_f32_e32 v41, v44, v41
	v_pk_fma_f32 v[34:35], v[34:35], 0.5, v[62:63] op_sel_hi:[1,0,1]
	v_pk_fma_f32 v[44:45], v[32:33], 0.5, v[60:61] op_sel_hi:[1,0,1]
	v_mul_f32_e32 v33, v35, v35
	v_mul_f32_e32 v32, v45, v45
	v_fmac_f32_e32 v32, v44, v44
	v_fmac_f32_e32 v33, v34, v34
	v_add_f32_e32 v32, v32, v33
	v_add_f32_e32 v32, v41, v32
	ds_bpermute_b32 v33, v178, v32
	v_cvt_pk_bf16_f32 v235, v42, v43
	s_nop 1
	v_permlane16_swap_b32 v232, v234
	v_permlane16_swap_b32 v233, v235
	v_lshl_add_u64 v[240:241], v[46:47], 0, v[242:243]
	global_store_dwordx4 v[240:241], v[232:235], off
	v_cvt_pk_bf16_f32 v236, v36, v37
	v_cvt_pk_bf16_f32 v237, v38, v39
	s_waitcnt lgkmcnt(0)
	v_add_f32_e32 v32, v32, v33
	ds_bpermute_b32 v33, v179, v32
	v_cvt_pk_bf16_f32 v238, v44, v45
	v_cvt_pk_bf16_f32 v239, v34, v35
	s_nop 1
	v_permlane16_swap_b32 v236, v238
	v_permlane16_swap_b32 v237, v239
	v_lshl_add_u64 v[240:241], v[46:47], 0, v[242:243]
	global_store_dwordx4 v[240:241], v[236:239], off offset:256
	s_and_saveexec_b64 s[50:51], s[6:7]
	s_cbranch_execz .LBB0_275
	s_waitcnt lgkmcnt(0)
	v_add_f32_e32 v32, v32, v33
	global_atomic_add_f32 v[112:113], v32, off offset:576
.LBB0_275:
	s_or_b64 exec, exec, s[50:51]
	v_lshlrev_b32_e32 v32, 16, v82
	s_waitcnt lgkmcnt(0)
	v_and_b32_e32 v33, 0xffff0000, v82
	v_lshlrev_b32_e32 v34, 16, v83
	v_and_b32_e32 v35, 0xffff0000, v83
	v_pk_fma_f32 v[30:31], v[30:31], 0.5, v[34:35] op_sel_hi:[1,0,1]
	v_pk_fma_f32 v[28:29], v[28:29], 0.5, v[32:33] op_sel_hi:[1,0,1]
	v_mul_f32_e32 v33, v31, v31
	v_mul_f32_e32 v32, v29, v29
	v_lshlrev_b32_e32 v36, 16, v80
	v_and_b32_e32 v37, 0xffff0000, v80
	v_lshlrev_b32_e32 v38, 16, v81
	v_and_b32_e32 v39, 0xffff0000, v81
	v_fmac_f32_e32 v32, v28, v28
	v_fmac_f32_e32 v33, v30, v30
	v_cvt_pk_bf16_f32 v232, v28, v29
	v_cvt_pk_bf16_f32 v233, v30, v31
	v_lshl_add_u64 v[30:31], s[34:35], 0, v[74:75]
	v_lshl_add_u64 v[30:31], v[140:141], 1, v[30:31]
	v_pk_fma_f32 v[26:27], v[26:27], 0.5, v[38:39] op_sel_hi:[1,0,1]
	v_pk_fma_f32 v[24:25], v[24:25], 0.5, v[36:37] op_sel_hi:[1,0,1]
	v_lshlrev_b32_e32 v40, 16, v78
	v_and_b32_e32 v41, 0xffff0000, v78
	v_lshlrev_b32_e32 v42, 16, v79
	v_and_b32_e32 v43, 0xffff0000, v79
	v_mul_f32_e32 v28, v25, v25
	v_mul_f32_e32 v29, v27, v27
	v_fmac_f32_e32 v28, v24, v24
	v_fmac_f32_e32 v29, v26, v26
	v_pk_fma_f32 v[22:23], v[22:23], 0.5, v[42:43] op_sel_hi:[1,0,1]
	v_pk_fma_f32 v[20:21], v[20:21], 0.5, v[40:41] op_sel_hi:[1,0,1]
	v_add_f32_e32 v28, v28, v29
	v_cvt_pk_bf16_f32 v234, v24, v25
	v_mul_f32_e32 v25, v21, v21
	v_mul_f32_e32 v29, v23, v23
	v_add_f32_e32 v32, v32, v33
	v_fmac_f32_e32 v25, v20, v20
	v_fmac_f32_e32 v29, v22, v22
	v_lshlrev_b32_e32 v44, 16, v76
	v_and_b32_e32 v45, 0xffff0000, v76
	v_lshlrev_b32_e32 v46, 16, v77
	v_and_b32_e32 v47, 0xffff0000, v77
	v_add_f32_e32 v28, v32, v28
	v_add_f32_e32 v25, v25, v29
	v_add_f32_e32 v25, v28, v25
	v_pk_fma_f32 v[18:19], v[18:19], 0.5, v[46:47] op_sel_hi:[1,0,1]
	v_pk_fma_f32 v[28:29], v[16:17], 0.5, v[44:45] op_sel_hi:[1,0,1]
	v_mul_f32_e32 v17, v19, v19
	v_mul_f32_e32 v16, v29, v29
	v_fmac_f32_e32 v16, v28, v28
	v_fmac_f32_e32 v17, v18, v18
	v_add_f32_e32 v16, v16, v17
	v_add_f32_e32 v16, v25, v16
	ds_bpermute_b32 v17, v178, v16
	v_cvt_pk_bf16_f32 v235, v26, v27
	s_nop 1
	v_permlane16_swap_b32 v232, v234
	v_permlane16_swap_b32 v233, v235
	v_lshl_add_u64 v[240:241], v[30:31], 0, v[242:243]
	global_store_dwordx4 v[240:241], v[232:235], off
	v_cvt_pk_bf16_f32 v236, v20, v21
	v_cvt_pk_bf16_f32 v237, v22, v23
	s_waitcnt lgkmcnt(0)
	v_add_f32_e32 v16, v16, v17
	ds_bpermute_b32 v17, v179, v16
	v_cvt_pk_bf16_f32 v238, v28, v29
	v_cvt_pk_bf16_f32 v239, v18, v19
	s_nop 1
	v_permlane16_swap_b32 v236, v238
	v_permlane16_swap_b32 v237, v239
	v_lshl_add_u64 v[240:241], v[30:31], 0, v[242:243]
	global_store_dwordx4 v[240:241], v[236:239], off offset:256
	s_and_saveexec_b64 s[50:51], s[6:7]
	s_cbranch_execz .LBB0_277
	s_waitcnt lgkmcnt(0)
	v_add_f32_e32 v16, v16, v17
	global_atomic_add_f32 v[112:113], v16, off offset:640
.LBB0_277:
	s_or_b64 exec, exec, s[50:51]
	v_lshlrev_b32_e32 v16, 16, v72
	s_waitcnt lgkmcnt(0)
	v_and_b32_e32 v17, 0xffff0000, v72
	v_lshlrev_b32_e32 v18, 16, v73
	v_and_b32_e32 v19, 0xffff0000, v73
	v_pk_fma_f32 v[14:15], v[14:15], 0.5, v[18:19] op_sel_hi:[1,0,1]
	v_pk_fma_f32 v[12:13], v[12:13], 0.5, v[16:17] op_sel_hi:[1,0,1]
	v_mul_f32_e32 v17, v15, v15
	v_mul_f32_e32 v16, v13, v13
	v_lshlrev_b32_e32 v20, 16, v70
	v_and_b32_e32 v21, 0xffff0000, v70
	v_lshlrev_b32_e32 v22, 16, v71
	v_and_b32_e32 v23, 0xffff0000, v71
	v_fmac_f32_e32 v16, v12, v12
	v_fmac_f32_e32 v17, v14, v14
	v_cvt_pk_bf16_f32 v232, v12, v13
	v_cvt_pk_bf16_f32 v233, v14, v15
	v_lshl_add_u64 v[14:15], s[34:35], 0, v[64:65]
	v_lshl_add_u64 v[14:15], v[140:141], 1, v[14:15]
	v_pk_fma_f32 v[10:11], v[10:11], 0.5, v[22:23] op_sel_hi:[1,0,1]
	v_pk_fma_f32 v[8:9], v[8:9], 0.5, v[20:21] op_sel_hi:[1,0,1]
	v_lshlrev_b32_e32 v24, 16, v68
	v_and_b32_e32 v25, 0xffff0000, v68
	v_lshlrev_b32_e32 v26, 16, v69
	v_and_b32_e32 v27, 0xffff0000, v69
	v_mul_f32_e32 v12, v9, v9
	v_mul_f32_e32 v13, v11, v11
	v_fmac_f32_e32 v12, v8, v8
	v_fmac_f32_e32 v13, v10, v10
	v_pk_fma_f32 v[6:7], v[6:7], 0.5, v[26:27] op_sel_hi:[1,0,1]
	v_pk_fma_f32 v[4:5], v[4:5], 0.5, v[24:25] op_sel_hi:[1,0,1]
	v_add_f32_e32 v12, v12, v13
	v_cvt_pk_bf16_f32 v234, v8, v9
	v_mul_f32_e32 v9, v5, v5
	v_mul_f32_e32 v13, v7, v7
	v_add_f32_e32 v16, v16, v17
	v_fmac_f32_e32 v9, v4, v4
	v_fmac_f32_e32 v13, v6, v6
	v_lshlrev_b32_e32 v28, 16, v66
	v_and_b32_e32 v29, 0xffff0000, v66
	v_lshlrev_b32_e32 v30, 16, v67
	v_and_b32_e32 v31, 0xffff0000, v67
	v_add_f32_e32 v12, v16, v12
	v_add_f32_e32 v9, v9, v13
	v_add_f32_e32 v9, v12, v9
	v_pk_fma_f32 v[2:3], v[2:3], 0.5, v[30:31] op_sel_hi:[1,0,1]
	v_pk_fma_f32 v[12:13], v[0:1], 0.5, v[28:29] op_sel_hi:[1,0,1]
	v_mul_f32_e32 v1, v3, v3
	v_mul_f32_e32 v0, v13, v13
	v_fmac_f32_e32 v0, v12, v12
	v_fmac_f32_e32 v1, v2, v2
	v_add_f32_e32 v0, v0, v1
	v_add_f32_e32 v0, v9, v0
	ds_bpermute_b32 v1, v178, v0
	v_cvt_pk_bf16_f32 v235, v10, v11
	s_nop 1
	v_permlane16_swap_b32 v232, v234
	v_permlane16_swap_b32 v233, v235
	v_lshl_add_u64 v[240:241], v[14:15], 0, v[242:243]
	global_store_dwordx4 v[240:241], v[232:235], off
	v_cvt_pk_bf16_f32 v236, v4, v5
	v_cvt_pk_bf16_f32 v237, v6, v7
	s_waitcnt lgkmcnt(0)
	v_add_f32_e32 v0, v0, v1
	ds_bpermute_b32 v1, v179, v0
	v_cvt_pk_bf16_f32 v238, v12, v13
	v_cvt_pk_bf16_f32 v239, v2, v3
	s_nop 1
	v_permlane16_swap_b32 v236, v238
	v_permlane16_swap_b32 v237, v239
	v_lshl_add_u64 v[240:241], v[14:15], 0, v[242:243]
	global_store_dwordx4 v[240:241], v[236:239], off offset:256
	s_and_saveexec_b64 s[50:51], s[6:7]
	s_cbranch_execz .LBB0_279
	s_waitcnt lgkmcnt(0)
	v_add_f32_e32 v0, v0, v1
	global_atomic_add_f32 v[112:113], v0, off offset:704

.LBB0_753:
	v_mbcnt_lo_u32_b32 v242, -1, 0
	v_mbcnt_hi_u32_b32 v242, -1, v242
	v_bfe_u32 v242, v242, 4, 1
	v_mul_u32_u24_e32 v242, 24, v242
	v_mov_b32_e32 v243, 0
	v_lshl_or_b32 v140, s42, 8, v186
	v_lshl_add_u32 v144, s40, 8, v182
	v_ashrrev_i32_e32 v141, 31, v140
	v_lshlrev_b64 v[190:191], 1, v[140:141]
	v_ashrrev_i32_e32 v145, 31, v144
	v_lshl_add_u64 v[142:143], s[34:35], 0, v[190:191]
	v_lshlrev_b64 v[192:193], 12, v[144:145]
	v_lshl_add_u64 v[146:147], v[142:143], 0, v[192:193]
	global_load_dwordx2 v[194:195], v[146:147], off
	global_load_dwordx2 v[196:197], v[146:147], off offset:32
	global_load_dwordx2 v[198:199], v[146:147], off offset:256
	global_load_dwordx2 v[200:201], v[146:147], off offset:288
	v_or_b32_e32 v162, 16, v144
	v_or_b32_e32 v150, 32, v144
	v_or_b32_e32 v146, 48, v144
	v_ashrrev_i32_e32 v163, 31, v162
	v_ashrrev_i32_e32 v151, 31, v150
	v_ashrrev_i32_e32 v147, 31, v146
	v_lshlrev_b64 v[172:173], 12, v[162:163]
	v_lshlrev_b64 v[160:161], 12, v[150:151]
	v_lshlrev_b64 v[148:149], 12, v[146:147]
	v_lshl_add_u64 v[152:153], v[142:143], 0, v[172:173]
	v_lshl_add_u64 v[154:155], v[142:143], 0, v[160:161]
	v_lshl_add_u64 v[202:203], v[142:143], 0, v[148:149]
	global_load_dwordx2 v[180:181], v[152:153], off
	global_load_dwordx2 v[178:179], v[152:153], off offset:32
	global_load_dwordx2 v[176:177], v[152:153], off offset:256
	global_load_dwordx2 v[174:175], v[152:153], off offset:288
	global_load_dwordx2 v[170:171], v[154:155], off
	global_load_dwordx2 v[168:169], v[154:155], off offset:32
	global_load_dwordx2 v[166:167], v[154:155], off offset:256
	global_load_dwordx2 v[164:165], v[154:155], off offset:288
	global_load_dwordx2 v[158:159], v[202:203], off
	global_load_dwordx2 v[156:157], v[202:203], off offset:32
	s_nop 0
	global_load_dwordx2 v[154:155], v[202:203], off offset:256
	global_load_dwordx2 v[152:153], v[202:203], off offset:288
	v_lshl_add_u64 v[192:193], s[34:35], 0, v[192:193]
	v_lshl_add_u64 v[190:191], v[192:193], 0, v[190:191]
	s_waitcnt vmcnt(0)
	v_lshlrev_b32_e32 v192, 16, v194
	v_and_b32_e32 v193, 0xffff0000, v194
	v_lshlrev_b32_e32 v194, 16, v195
	v_and_b32_e32 v195, 0xffff0000, v195
	v_lshlrev_b32_e32 v202, 16, v196
	v_and_b32_e32 v203, 0xffff0000, v196
	v_lshlrev_b32_e32 v196, 16, v197
	v_and_b32_e32 v197, 0xffff0000, v197
	v_lshlrev_b32_e32 v204, 16, v198
	v_and_b32_e32 v205, 0xffff0000, v198
	v_lshlrev_b32_e32 v198, 16, v199
	v_and_b32_e32 v199, 0xffff0000, v199
	v_lshlrev_b32_e32 v206, 16, v200
	v_and_b32_e32 v207, 0xffff0000, v200
	v_pk_add_f32 v[126:127], v[126:127], v[194:195]
	v_pk_add_f32 v[124:125], v[124:125], v[192:193]
	v_pk_add_f32 v[122:123], v[122:123], v[196:197]
	v_pk_add_f32 v[120:121], v[120:121], v[202:203]
	v_lshlrev_b32_e32 v200, 16, v201
	v_and_b32_e32 v201, 0xffff0000, v201
	v_pk_add_f32 v[118:119], v[118:119], v[198:199]
	v_pk_add_f32 v[116:117], v[116:117], v[204:205]
	v_pk_add_f32 v[192:193], v[112:113], v[206:207]
	v_mul_f32_e32 v194, v125, v125
	v_mul_f32_e32 v195, v127, v127
	v_cvt_pk_bf16_f32 v232, v124, v125
	v_cvt_pk_bf16_f32 v233, v126, v127
	v_mul_f32_e32 v125, v121, v121
	v_mul_f32_e32 v127, v123, v123
	v_pk_add_f32 v[114:115], v[114:115], v[200:201]
	v_mul_f32_e32 v196, v117, v117
	v_mul_f32_e32 v197, v119, v119
	v_fmac_f32_e32 v194, v124, v124
	v_fmac_f32_e32 v195, v126, v126
	v_fmac_f32_e32 v125, v120, v120
	v_fmac_f32_e32 v127, v122, v122
	v_mul_f32_e32 v198, v193, v193
	v_mul_f32_e32 v199, v115, v115
	v_cvt_pk_bf16_f32 v234, v120, v121
	v_fmac_f32_e32 v196, v116, v116
	v_fmac_f32_e32 v197, v118, v118
	v_add_f32_e32 v113, v194, v195
	v_add_f32_e32 v120, v125, v127
	v_fmac_f32_e32 v198, v192, v192
	v_fmac_f32_e32 v199, v114, v114
	v_add_f32_e32 v121, v196, v197
	v_add_f32_e32 v113, v113, v120
	v_add_f32_e32 v113, v113, v121
	v_add_f32_e32 v120, v198, v199
	v_add_f32_e32 v120, v113, v120
	ds_bpermute_b32 v121, v184, v120
	v_cvt_pk_bf16_f32 v235, v122, v123
	s_nop 1
	v_permlane16_swap_b32 v232, v234
	v_permlane16_swap_b32 v233, v235
	v_lshl_add_u64 v[240:241], v[190:191], 0, v[242:243]
	global_store_dwordx4 v[240:241], v[232:235], off
	v_cvt_pk_bf16_f32 v236, v116, v117
	v_cvt_pk_bf16_f32 v237, v118, v119
	s_waitcnt lgkmcnt(0)
	v_add_f32_e32 v112, v120, v121
	ds_bpermute_b32 v113, v185, v112
	v_cvt_pk_bf16_f32 v238, v192, v193
	v_cvt_pk_bf16_f32 v239, v114, v115
	s_nop 1
	v_permlane16_swap_b32 v236, v238
	v_permlane16_swap_b32 v237, v239
	v_lshl_add_u64 v[240:241], v[190:191], 0, v[242:243]
	global_store_dwordx4 v[240:241], v[236:239], off offset:256
	s_and_saveexec_b64 s[40:41], s[8:9]
	s_cbranch_execz .LBB0_755
	v_lshl_add_u64 v[114:115], v[144:145], 2, s[12:13]
	s_waitcnt lgkmcnt(0)
	v_add_f32_e32 v112, v112, v113
	global_atomic_add_f32 v[114:115], v112, off
.LBB0_755:
	s_or_b64 exec, exec, s[40:41]
	v_lshlrev_b32_e32 v112, 16, v180
	s_waitcnt lgkmcnt(0)
	v_and_b32_e32 v113, 0xffff0000, v180
	v_lshlrev_b32_e32 v114, 16, v181
	v_and_b32_e32 v115, 0xffff0000, v181
	v_pk_add_f32 v[110:111], v[110:111], v[114:115]
	v_pk_add_f32 v[108:109], v[108:109], v[112:113]
	v_mul_f32_e32 v113, v111, v111
	v_mul_f32_e32 v112, v109, v109
	v_lshlrev_b32_e32 v116, 16, v178
	v_and_b32_e32 v117, 0xffff0000, v178
	v_lshlrev_b32_e32 v118, 16, v179
	v_and_b32_e32 v119, 0xffff0000, v179
	v_fmac_f32_e32 v112, v108, v108
	v_fmac_f32_e32 v113, v110, v110
	v_cvt_pk_bf16_f32 v232, v108, v109
	v_cvt_pk_bf16_f32 v233, v110, v111
	v_lshl_add_u64 v[110:111], s[34:35], 0, v[172:173]
	v_lshl_add_u64 v[110:111], v[140:141], 1, v[110:111]
	v_pk_add_f32 v[106:107], v[106:107], v[118:119]
	v_pk_add_f32 v[104:105], v[104:105], v[116:117]
	v_lshlrev_b32_e32 v120, 16, v176
	v_and_b32_e32 v121, 0xffff0000, v176
	v_lshlrev_b32_e32 v122, 16, v177
	v_and_b32_e32 v123, 0xffff0000, v177
	v_mul_f32_e32 v108, v105, v105
	v_mul_f32_e32 v109, v107, v107
	v_fmac_f32_e32 v108, v104, v104
	v_fmac_f32_e32 v109, v106, v106
	v_pk_add_f32 v[102:103], v[102:103], v[122:123]
	v_pk_add_f32 v[100:101], v[100:101], v[120:121]
	v_add_f32_e32 v108, v108, v109
	v_cvt_pk_bf16_f32 v234, v104, v105
	v_mul_f32_e32 v105, v101, v101
	v_mul_f32_e32 v109, v103, v103
	v_add_f32_e32 v112, v112, v113
	v_fmac_f32_e32 v105, v100, v100
	v_fmac_f32_e32 v109, v102, v102
	v_lshlrev_b32_e32 v124, 16, v174
	v_and_b32_e32 v125, 0xffff0000, v174
	v_lshlrev_b32_e32 v126, 16, v175
	v_and_b32_e32 v127, 0xffff0000, v175
	v_add_f32_e32 v108, v112, v108
	v_add_f32_e32 v105, v105, v109
	v_add_f32_e32 v105, v108, v105
	v_pk_add_f32 v[98:99], v[98:99], v[126:127]
	v_pk_add_f32 v[108:109], v[96:97], v[124:125]
	v_mul_f32_e32 v97, v99, v99
	v_mul_f32_e32 v96, v109, v109
	v_fmac_f32_e32 v96, v108, v108
	v_fmac_f32_e32 v97, v98, v98
	v_add_f32_e32 v96, v96, v97
	v_add_f32_e32 v96, v105, v96
	ds_bpermute_b32 v97, v184, v96
	v_cvt_pk_bf16_f32 v235, v106, v107
	s_nop 1
	v_permlane16_swap_b32 v232, v234
	v_permlane16_swap_b32 v233, v235
	v_lshl_add_u64 v[240:241], v[110:111], 0, v[242:243]
	global_store_dwordx4 v[240:241], v[232:235], off
	v_cvt_pk_bf16_f32 v236, v100, v101
	v_cvt_pk_bf16_f32 v237, v102, v103
	s_waitcnt lgkmcnt(0)
	v_add_f32_e32 v96, v96, v97
	ds_bpermute_b32 v97, v185, v96
	v_cvt_pk_bf16_f32 v238, v108, v109
	v_cvt_pk_bf16_f32 v239, v98, v99
	s_nop 1
	v_permlane16_swap_b32 v236, v238
	v_permlane16_swap_b32 v237, v239
	v_lshl_add_u64 v[240:241], v[110:111], 0, v[242:243]
	global_store_dwordx4 v[240:241], v[236:239], off offset:256
	s_and_saveexec_b64 s[40:41], s[8:9]
	s_cbranch_execz .LBB0_757
	v_lshl_add_u64 v[98:99], v[162:163], 2, s[12:13]
	s_waitcnt lgkmcnt(0)
	v_add_f32_e32 v96, v96, v97
	global_atomic_add_f32 v[98:99], v96, off
.LBB0_757:
	s_or_b64 exec, exec, s[40:41]
	v_lshlrev_b32_e32 v96, 16, v170
	s_waitcnt lgkmcnt(0)
	v_and_b32_e32 v97, 0xffff0000, v170
	v_lshlrev_b32_e32 v98, 16, v171
	v_and_b32_e32 v99, 0xffff0000, v171
	v_pk_add_f32 v[94:95], v[94:95], v[98:99]
	v_pk_add_f32 v[92:93], v[92:93], v[96:97]
	v_mul_f32_e32 v97, v95, v95
	v_mul_f32_e32 v96, v93, v93
	v_lshlrev_b32_e32 v100, 16, v168
	v_and_b32_e32 v101, 0xffff0000, v168
	v_lshlrev_b32_e32 v102, 16, v169
	v_and_b32_e32 v103, 0xffff0000, v169
	v_fmac_f32_e32 v96, v92, v92
	v_fmac_f32_e32 v97, v94, v94
	v_cvt_pk_bf16_f32 v232, v92, v93
	v_cvt_pk_bf16_f32 v233, v94, v95
	v_lshl_add_u64 v[94:95], s[34:35], 0, v[160:161]
	v_lshl_add_u64 v[94:95], v[140:141], 1, v[94:95]
	v_pk_add_f32 v[90:91], v[90:91], v[102:103]
	v_pk_add_f32 v[88:89], v[88:89], v[100:101]
	v_lshlrev_b32_e32 v104, 16, v166
	v_and_b32_e32 v105, 0xffff0000, v166
	v_lshlrev_b32_e32 v106, 16, v167
	v_and_b32_e32 v107, 0xffff0000, v167
	v_mul_f32_e32 v92, v89, v89
	v_mul_f32_e32 v93, v91, v91
	v_fmac_f32_e32 v92, v88, v88
	v_fmac_f32_e32 v93, v90, v90
	v_pk_add_f32 v[86:87], v[86:87], v[106:107]
	v_pk_add_f32 v[84:85], v[84:85], v[104:105]
	v_add_f32_e32 v92, v92, v93
	v_cvt_pk_bf16_f32 v234, v88, v89
	v_mul_f32_e32 v89, v85, v85
	v_mul_f32_e32 v93, v87, v87
	v_add_f32_e32 v96, v96, v97
	v_fmac_f32_e32 v89, v84, v84
	v_fmac_f32_e32 v93, v86, v86
	v_lshlrev_b32_e32 v108, 16, v164
	v_and_b32_e32 v109, 0xffff0000, v164
	v_lshlrev_b32_e32 v110, 16, v165
	v_and_b32_e32 v111, 0xffff0000, v165
	v_add_f32_e32 v92, v96, v92
	v_add_f32_e32 v89, v89, v93
	v_add_f32_e32 v89, v92, v89
	v_pk_add_f32 v[82:83], v[82:83], v[110:111]
	v_pk_add_f32 v[92:93], v[80:81], v[108:109]
	v_mul_f32_e32 v81, v83, v83
	v_mul_f32_e32 v80, v93, v93
	v_fmac_f32_e32 v80, v92, v92
	v_fmac_f32_e32 v81, v82, v82
	v_add_f32_e32 v80, v80, v81
	v_add_f32_e32 v80, v89, v80
	ds_bpermute_b32 v81, v184, v80
	v_cvt_pk_bf16_f32 v235, v90, v91
	s_nop 1
	v_permlane16_swap_b32 v232, v234
	v_permlane16_swap_b32 v233, v235
	v_lshl_add_u64 v[240:241], v[94:95], 0, v[242:243]
	global_store_dwordx4 v[240:241], v[232:235], off
	v_cvt_pk_bf16_f32 v236, v84, v85
	v_cvt_pk_bf16_f32 v237, v86, v87
	s_waitcnt lgkmcnt(0)
	v_add_f32_e32 v80, v80, v81
	ds_bpermute_b32 v81, v185, v80
	v_cvt_pk_bf16_f32 v238, v92, v93
	v_cvt_pk_bf16_f32 v239, v82, v83
	s_nop 1
	v_permlane16_swap_b32 v236, v238
	v_permlane16_swap_b32 v237, v239
	v_lshl_add_u64 v[240:241], v[94:95], 0, v[242:243]
	global_store_dwordx4 v[240:241], v[236:239], off offset:256
	s_and_saveexec_b64 s[40:41], s[8:9]
	s_cbranch_execz .LBB0_759
	v_lshl_add_u64 v[82:83], v[150:151], 2, s[12:13]
	s_waitcnt lgkmcnt(0)
	v_add_f32_e32 v80, v80, v81
	global_atomic_add_f32 v[82:83], v80, off
.LBB0_759:
	s_or_b64 exec, exec, s[40:41]
	v_lshlrev_b32_e32 v80, 16, v158
	s_waitcnt lgkmcnt(0)
	v_and_b32_e32 v81, 0xffff0000, v158
	v_lshlrev_b32_e32 v82, 16, v159
	v_and_b32_e32 v83, 0xffff0000, v159
	v_pk_add_f32 v[78:79], v[78:79], v[82:83]
	v_pk_add_f32 v[76:77], v[76:77], v[80:81]
	v_mul_f32_e32 v81, v79, v79
	v_mul_f32_e32 v80, v77, v77
	v_lshlrev_b32_e32 v84, 16, v156
	v_and_b32_e32 v85, 0xffff0000, v156
	v_lshlrev_b32_e32 v86, 16, v157
	v_and_b32_e32 v87, 0xffff0000, v157
	v_fmac_f32_e32 v80, v76, v76
	v_fmac_f32_e32 v81, v78, v78
	v_cvt_pk_bf16_f32 v232, v76, v77
	v_cvt_pk_bf16_f32 v233, v78, v79
	v_lshl_add_u64 v[78:79], s[34:35], 0, v[148:149]
	v_lshl_add_u64 v[78:79], v[140:141], 1, v[78:79]
	v_pk_add_f32 v[74:75], v[74:75], v[86:87]
	v_pk_add_f32 v[72:73], v[72:73], v[84:85]
	v_lshlrev_b32_e32 v88, 16, v154
	v_and_b32_e32 v89, 0xffff0000, v154
	v_lshlrev_b32_e32 v90, 16, v155
	v_and_b32_e32 v91, 0xffff0000, v155
	v_mul_f32_e32 v76, v73, v73
	v_mul_f32_e32 v77, v75, v75
	v_fmac_f32_e32 v76, v72, v72
	v_fmac_f32_e32 v77, v74, v74
	v_pk_add_f32 v[70:71], v[70:71], v[90:91]
	v_pk_add_f32 v[68:69], v[68:69], v[88:89]
	v_add_f32_e32 v76, v76, v77
	v_cvt_pk_bf16_f32 v234, v72, v73
	v_mul_f32_e32 v73, v69, v69
	v_mul_f32_e32 v77, v71, v71
	v_add_f32_e32 v80, v80, v81
	v_fmac_f32_e32 v73, v68, v68
	v_fmac_f32_e32 v77, v70, v70
	v_lshlrev_b32_e32 v92, 16, v152
	v_and_b32_e32 v93, 0xffff0000, v152
	v_lshlrev_b32_e32 v94, 16, v153
	v_and_b32_e32 v95, 0xffff0000, v153
	v_add_f32_e32 v76, v80, v76
	v_add_f32_e32 v73, v73, v77
	v_add_f32_e32 v73, v76, v73
	v_pk_add_f32 v[66:67], v[66:67], v[94:95]
	v_pk_add_f32 v[76:77], v[64:65], v[92:93]
	v_mul_f32_e32 v65, v67, v67
	v_mul_f32_e32 v64, v77, v77
	v_fmac_f32_e32 v64, v76, v76
	v_fmac_f32_e32 v65, v66, v66
	v_add_f32_e32 v64, v64, v65
	v_add_f32_e32 v64, v73, v64
	ds_bpermute_b32 v65, v184, v64
	v_cvt_pk_bf16_f32 v235, v74, v75
	s_nop 1
	v_permlane16_swap_b32 v232, v234
	v_permlane16_swap_b32 v233, v235
	v_lshl_add_u64 v[240:241], v[78:79], 0, v[242:243]
	global_store_dwordx4 v[240:241], v[232:235], off
	v_cvt_pk_bf16_f32 v236, v68, v69
	v_cvt_pk_bf16_f32 v237, v70, v71
	s_waitcnt lgkmcnt(0)
	v_add_f32_e32 v64, v64, v65
	ds_bpermute_b32 v65, v185, v64
	v_cvt_pk_bf16_f32 v238, v76, v77
	v_cvt_pk_bf16_f32 v239, v66, v67
	s_nop 1
	v_permlane16_swap_b32 v236, v238
	v_permlane16_swap_b32 v237, v239
	v_lshl_add_u64 v[240:241], v[78:79], 0, v[242:243]
	global_store_dwordx4 v[240:241], v[236:239], off offset:256
	s_and_saveexec_b64 s[40:41], s[8:9]
	s_cbranch_execz .LBB0_761
	v_lshl_add_u64 v[66:67], v[146:147], 2, s[12:13]
	s_waitcnt lgkmcnt(0)
	v_add_f32_e32 v64, v64, v65
	global_atomic_add_f32 v[66:67], v64, off
.LBB0_761:
	s_or_b64 exec, exec, s[40:41]
	v_add_u32_e32 v90, 0x80, v144
	v_ashrrev_i32_e32 v91, 31, v90
	v_lshlrev_b64 v[102:103], 12, v[90:91]
	s_waitcnt lgkmcnt(0)
	v_lshl_add_u64 v[64:65], v[142:143], 0, v[102:103]
	global_load_dwordx2 v[104:105], v[64:65], off
	global_load_dwordx2 v[106:107], v[64:65], off offset:32
	global_load_dwordx2 v[108:109], v[64:65], off offset:256
	global_load_dwordx2 v[110:111], v[64:65], off offset:288
	v_add_u32_e32 v80, 0x90, v144
	v_add_u32_e32 v68, 0xa0, v144
	v_add_u32_e32 v64, 0xb0, v144
	v_ashrrev_i32_e32 v81, 31, v80
	v_ashrrev_i32_e32 v69, 31, v68
	v_ashrrev_i32_e32 v65, 31, v64
	v_lshlrev_b64 v[92:93], 12, v[80:81]
	v_lshlrev_b64 v[78:79], 12, v[68:69]
	v_lshlrev_b64 v[66:67], 12, v[64:65]
	v_lshl_add_u64 v[70:71], v[142:143], 0, v[92:93]
	v_lshl_add_u64 v[72:73], v[142:143], 0, v[78:79]
	v_lshl_add_u64 v[112:113], v[142:143], 0, v[66:67]
	global_load_dwordx2 v[100:101], v[70:71], off
	global_load_dwordx2 v[98:99], v[70:71], off offset:32
	global_load_dwordx2 v[96:97], v[70:71], off offset:256
	global_load_dwordx2 v[94:95], v[70:71], off offset:288
	global_load_dwordx2 v[88:89], v[72:73], off
	global_load_dwordx2 v[86:87], v[72:73], off offset:32
	global_load_dwordx2 v[84:85], v[72:73], off offset:256
	global_load_dwordx2 v[82:83], v[72:73], off offset:288
	global_load_dwordx2 v[76:77], v[112:113], off
	global_load_dwordx2 v[74:75], v[112:113], off offset:32
	s_nop 0
	global_load_dwordx2 v[72:73], v[112:113], off offset:256
	global_load_dwordx2 v[70:71], v[112:113], off offset:288
	v_lshl_add_u64 v[102:103], s[34:35], 0, v[102:103]
	v_lshl_add_u64 v[102:103], v[140:141], 1, v[102:103]
	s_waitcnt vmcnt(15)
	v_lshlrev_b32_e32 v112, 16, v104
	v_and_b32_e32 v113, 0xffff0000, v104
	v_lshlrev_b32_e32 v104, 16, v105
	v_and_b32_e32 v105, 0xffff0000, v105
	s_waitcnt vmcnt(14)
	v_lshlrev_b32_e32 v114, 16, v106
	v_and_b32_e32 v115, 0xffff0000, v106
	v_lshlrev_b32_e32 v106, 16, v107
	v_and_b32_e32 v107, 0xffff0000, v107
	s_waitcnt vmcnt(13)
	v_lshlrev_b32_e32 v116, 16, v108
	v_and_b32_e32 v117, 0xffff0000, v108
	v_lshlrev_b32_e32 v108, 16, v109
	v_and_b32_e32 v109, 0xffff0000, v109
	s_waitcnt vmcnt(12)
	v_lshlrev_b32_e32 v118, 16, v110
	v_and_b32_e32 v119, 0xffff0000, v110
	v_pk_add_f32 v[62:63], v[62:63], v[104:105]
	v_pk_add_f32 v[60:61], v[60:61], v[112:113]
	v_pk_add_f32 v[58:59], v[58:59], v[106:107]
	v_pk_add_f32 v[56:57], v[56:57], v[114:115]
	v_lshlrev_b32_e32 v110, 16, v111
	v_and_b32_e32 v111, 0xffff0000, v111
	v_pk_add_f32 v[54:55], v[54:55], v[108:109]
	v_pk_add_f32 v[52:53], v[52:53], v[116:117]
	v_pk_add_f32 v[104:105], v[48:49], v[118:119]
	v_mul_f32_e32 v106, v61, v61
	v_mul_f32_e32 v107, v63, v63
	v_cvt_pk_bf16_f32 v232, v60, v61
	v_cvt_pk_bf16_f32 v233, v62, v63
	v_mul_f32_e32 v61, v57, v57
	v_mul_f32_e32 v63, v59, v59
	v_pk_add_f32 v[50:51], v[50:51], v[110:111]
	v_mul_f32_e32 v108, v53, v53
	v_mul_f32_e32 v109, v55, v55
	v_fmac_f32_e32 v106, v60, v60
	v_fmac_f32_e32 v107, v62, v62
	v_fmac_f32_e32 v61, v56, v56
	v_fmac_f32_e32 v63, v58, v58
	v_mul_f32_e32 v110, v105, v105
	v_mul_f32_e32 v111, v51, v51
	v_cvt_pk_bf16_f32 v234, v56, v57
	v_fmac_f32_e32 v108, v52, v52
	v_fmac_f32_e32 v109, v54, v54
	v_add_f32_e32 v49, v106, v107
	v_add_f32_e32 v56, v61, v63
	v_fmac_f32_e32 v110, v104, v104
	v_fmac_f32_e32 v111, v50, v50
	v_add_f32_e32 v57, v108, v109
	v_add_f32_e32 v49, v49, v56
	v_add_f32_e32 v49, v49, v57
	v_add_f32_e32 v56, v110, v111
	v_add_f32_e32 v56, v49, v56
	ds_bpermute_b32 v57, v184, v56
	v_cvt_pk_bf16_f32 v235, v58, v59
	s_nop 1
	v_permlane16_swap_b32 v232, v234
	v_permlane16_swap_b32 v233, v235
	v_lshl_add_u64 v[240:241], v[102:103], 0, v[242:243]
	global_store_dwordx4 v[240:241], v[232:235], off
	v_cvt_pk_bf16_f32 v236, v52, v53
	v_cvt_pk_bf16_f32 v237, v54, v55
	s_waitcnt lgkmcnt(0)
	v_add_f32_e32 v48, v56, v57
	ds_bpermute_b32 v49, v185, v48
	v_cvt_pk_bf16_f32 v238, v104, v105
	v_cvt_pk_bf16_f32 v239, v50, v51
	s_nop 1
	v_permlane16_swap_b32 v236, v238
	v_permlane16_swap_b32 v237, v239
	v_lshl_add_u64 v[240:241], v[102:103], 0, v[242:243]
	global_store_dwordx4 v[240:241], v[236:239], off offset:256
	s_and_saveexec_b64 s[40:41], s[8:9]
	s_cbranch_execz .LBB0_763
	v_lshl_add_u64 v[50:51], v[90:91], 2, s[12:13]
	s_waitcnt lgkmcnt(0)
	v_add_f32_e32 v48, v48, v49
	global_atomic_add_f32 v[50:51], v48, off
.LBB0_763:
	s_or_b64 exec, exec, s[40:41]
	s_waitcnt vmcnt(13)
	v_lshlrev_b32_e32 v48, 16, v100
	s_waitcnt lgkmcnt(0)
	v_and_b32_e32 v49, 0xffff0000, v100
	v_lshlrev_b32_e32 v50, 16, v101
	v_and_b32_e32 v51, 0xffff0000, v101
	v_pk_add_f32 v[46:47], v[46:47], v[50:51]
	v_pk_add_f32 v[44:45], v[44:45], v[48:49]
	v_mul_f32_e32 v49, v47, v47
	v_mul_f32_e32 v48, v45, v45
	s_waitcnt vmcnt(12)
	v_lshlrev_b32_e32 v52, 16, v98
	v_and_b32_e32 v53, 0xffff0000, v98
	v_lshlrev_b32_e32 v54, 16, v99
	v_and_b32_e32 v55, 0xffff0000, v99
	v_fmac_f32_e32 v48, v44, v44
	v_fmac_f32_e32 v49, v46, v46
	v_cvt_pk_bf16_f32 v232, v44, v45
	v_cvt_pk_bf16_f32 v233, v46, v47
	v_lshl_add_u64 v[46:47], s[34:35], 0, v[92:93]
	v_lshl_add_u64 v[46:47], v[140:141], 1, v[46:47]
	v_pk_add_f32 v[42:43], v[42:43], v[54:55]
	v_pk_add_f32 v[40:41], v[40:41], v[52:53]
	s_waitcnt vmcnt(11)
	v_lshlrev_b32_e32 v56, 16, v96
	v_and_b32_e32 v57, 0xffff0000, v96
	v_lshlrev_b32_e32 v58, 16, v97
	v_and_b32_e32 v59, 0xffff0000, v97
	v_mul_f32_e32 v44, v41, v41
	v_mul_f32_e32 v45, v43, v43
	v_fmac_f32_e32 v44, v40, v40
	v_fmac_f32_e32 v45, v42, v42
	v_pk_add_f32 v[38:39], v[38:39], v[58:59]
	v_pk_add_f32 v[36:37], v[36:37], v[56:57]
	v_add_f32_e32 v44, v44, v45
	v_cvt_pk_bf16_f32 v234, v40, v41
	v_mul_f32_e32 v41, v37, v37
	v_mul_f32_e32 v45, v39, v39
	v_add_f32_e32 v48, v48, v49
	v_fmac_f32_e32 v41, v36, v36
	v_fmac_f32_e32 v45, v38, v38
	s_waitcnt vmcnt(10)
	v_lshlrev_b32_e32 v60, 16, v94
	v_and_b32_e32 v61, 0xffff0000, v94
	v_lshlrev_b32_e32 v62, 16, v95
	v_and_b32_e32 v63, 0xffff0000, v95
	v_add_f32_e32 v44, v48, v44
	v_add_f32_e32 v41, v41, v45
	v_add_f32_e32 v41, v44, v41
	v_pk_add_f32 v[34:35], v[34:35], v[62:63]
	v_pk_add_f32 v[44:45], v[32:33], v[60:61]
	v_mul_f32_e32 v33, v35, v35
	v_mul_f32_e32 v32, v45, v45
	v_fmac_f32_e32 v32, v44, v44
	v_fmac_f32_e32 v33, v34, v34
	v_add_f32_e32 v32, v32, v33
	v_add_f32_e32 v32, v41, v32
	ds_bpermute_b32 v33, v184, v32
	v_cvt_pk_bf16_f32 v235, v42, v43
	s_nop 1
	v_permlane16_swap_b32 v232, v234
	v_permlane16_swap_b32 v233, v235
	v_lshl_add_u64 v[240:241], v[46:47], 0, v[242:243]
	global_store_dwordx4 v[240:241], v[232:235], off
	v_cvt_pk_bf16_f32 v236, v36, v37
	v_cvt_pk_bf16_f32 v237, v38, v39
	s_waitcnt lgkmcnt(0)
	v_add_f32_e32 v32, v32, v33
	ds_bpermute_b32 v33, v185, v32
	v_cvt_pk_bf16_f32 v238, v44, v45
	v_cvt_pk_bf16_f32 v239, v34, v35
	s_nop 1
	v_permlane16_swap_b32 v236, v238
	v_permlane16_swap_b32 v237, v239
	v_lshl_add_u64 v[240:241], v[46:47], 0, v[242:243]
	global_store_dwordx4 v[240:241], v[236:239], off offset:256
	s_and_saveexec_b64 s[40:41], s[8:9]
	s_cbranch_execz .LBB0_765
	v_lshl_add_u64 v[34:35], v[80:81], 2, s[12:13]
	s_waitcnt lgkmcnt(0)
	v_add_f32_e32 v32, v32, v33
	global_atomic_add_f32 v[34:35], v32, off
.LBB0_765:
	s_or_b64 exec, exec, s[40:41]
	s_waitcnt vmcnt(11)
	v_lshlrev_b32_e32 v32, 16, v88
	s_waitcnt lgkmcnt(0)
	v_and_b32_e32 v33, 0xffff0000, v88
	v_lshlrev_b32_e32 v34, 16, v89
	v_and_b32_e32 v35, 0xffff0000, v89
	v_pk_add_f32 v[30:31], v[30:31], v[34:35]
	v_pk_add_f32 v[28:29], v[28:29], v[32:33]
	v_mul_f32_e32 v33, v31, v31
	v_mul_f32_e32 v32, v29, v29
	s_waitcnt vmcnt(10)
	v_lshlrev_b32_e32 v36, 16, v86
	v_and_b32_e32 v37, 0xffff0000, v86
	v_lshlrev_b32_e32 v38, 16, v87
	v_and_b32_e32 v39, 0xffff0000, v87
	v_fmac_f32_e32 v32, v28, v28
	v_fmac_f32_e32 v33, v30, v30
	v_cvt_pk_bf16_f32 v232, v28, v29
	v_cvt_pk_bf16_f32 v233, v30, v31
	v_lshl_add_u64 v[30:31], s[34:35], 0, v[78:79]
	v_lshl_add_u64 v[30:31], v[140:141], 1, v[30:31]
	v_pk_add_f32 v[26:27], v[26:27], v[38:39]
	v_pk_add_f32 v[24:25], v[24:25], v[36:37]
	s_waitcnt vmcnt(9)
	v_lshlrev_b32_e32 v40, 16, v84
	v_and_b32_e32 v41, 0xffff0000, v84
	v_lshlrev_b32_e32 v42, 16, v85
	v_and_b32_e32 v43, 0xffff0000, v85
	v_mul_f32_e32 v28, v25, v25
	v_mul_f32_e32 v29, v27, v27
	v_fmac_f32_e32 v28, v24, v24
	v_fmac_f32_e32 v29, v26, v26
	v_pk_add_f32 v[22:23], v[22:23], v[42:43]
	v_pk_add_f32 v[20:21], v[20:21], v[40:41]
	v_add_f32_e32 v28, v28, v29
	v_cvt_pk_bf16_f32 v234, v24, v25
	v_mul_f32_e32 v25, v21, v21
	v_mul_f32_e32 v29, v23, v23
	v_add_f32_e32 v32, v32, v33
	v_fmac_f32_e32 v25, v20, v20
	v_fmac_f32_e32 v29, v22, v22
	s_waitcnt vmcnt(8)
	v_lshlrev_b32_e32 v44, 16, v82
	v_and_b32_e32 v45, 0xffff0000, v82
	v_lshlrev_b32_e32 v46, 16, v83
	v_and_b32_e32 v47, 0xffff0000, v83
	v_add_f32_e32 v28, v32, v28
	v_add_f32_e32 v25, v25, v29
	v_add_f32_e32 v25, v28, v25
	v_pk_add_f32 v[18:19], v[18:19], v[46:47]
	v_pk_add_f32 v[28:29], v[16:17], v[44:45]
	v_mul_f32_e32 v17, v19, v19
	v_mul_f32_e32 v16, v29, v29
	v_fmac_f32_e32 v16, v28, v28
	v_fmac_f32_e32 v17, v18, v18
	v_add_f32_e32 v16, v16, v17
	v_add_f32_e32 v16, v25, v16
	ds_bpermute_b32 v17, v184, v16
	v_cvt_pk_bf16_f32 v235, v26, v27
	s_nop 1
	v_permlane16_swap_b32 v232, v234
	v_permlane16_swap_b32 v233, v235
	v_lshl_add_u64 v[240:241], v[30:31], 0, v[242:243]
	global_store_dwordx4 v[240:241], v[232:235], off
	v_cvt_pk_bf16_f32 v236, v20, v21
	v_cvt_pk_bf16_f32 v237, v22, v23
	s_waitcnt lgkmcnt(0)
	v_add_f32_e32 v16, v16, v17
	ds_bpermute_b32 v17, v185, v16
	v_cvt_pk_bf16_f32 v238, v28, v29
	v_cvt_pk_bf16_f32 v239, v18, v19
	s_nop 1
	v_permlane16_swap_b32 v236, v238
	v_permlane16_swap_b32 v237, v239
	v_lshl_add_u64 v[240:241], v[30:31], 0, v[242:243]
	global_store_dwordx4 v[240:241], v[236:239], off offset:256
	s_and_saveexec_b64 s[40:41], s[8:9]
	s_cbranch_execz .LBB0_767
	v_lshl_add_u64 v[18:19], v[68:69], 2, s[12:13]
	s_waitcnt lgkmcnt(0)
	v_add_f32_e32 v16, v16, v17
	global_atomic_add_f32 v[18:19], v16, off
.LBB0_767:
	s_or_b64 exec, exec, s[40:41]
	s_waitcnt vmcnt(9)
	v_lshlrev_b32_e32 v16, 16, v76
	s_waitcnt lgkmcnt(0)
	v_and_b32_e32 v17, 0xffff0000, v76
	v_lshlrev_b32_e32 v18, 16, v77
	v_and_b32_e32 v19, 0xffff0000, v77
	v_pk_add_f32 v[14:15], v[14:15], v[18:19]
	v_pk_add_f32 v[12:13], v[12:13], v[16:17]
	v_mul_f32_e32 v17, v15, v15
	v_mul_f32_e32 v16, v13, v13
	s_waitcnt vmcnt(8)
	v_lshlrev_b32_e32 v20, 16, v74
	v_and_b32_e32 v21, 0xffff0000, v74
	v_lshlrev_b32_e32 v22, 16, v75
	v_and_b32_e32 v23, 0xffff0000, v75
	v_fmac_f32_e32 v16, v12, v12
	v_fmac_f32_e32 v17, v14, v14
	v_cvt_pk_bf16_f32 v232, v12, v13
	v_cvt_pk_bf16_f32 v233, v14, v15
	v_lshl_add_u64 v[14:15], s[34:35], 0, v[66:67]
	v_lshl_add_u64 v[14:15], v[140:141], 1, v[14:15]
	v_pk_add_f32 v[10:11], v[10:11], v[22:23]
	v_pk_add_f32 v[8:9], v[8:9], v[20:21]
	s_waitcnt vmcnt(7)
	v_lshlrev_b32_e32 v24, 16, v72
	v_and_b32_e32 v25, 0xffff0000, v72
	v_lshlrev_b32_e32 v26, 16, v73
	v_and_b32_e32 v27, 0xffff0000, v73
	v_mul_f32_e32 v12, v9, v9
	v_mul_f32_e32 v13, v11, v11
	v_fmac_f32_e32 v12, v8, v8
	v_fmac_f32_e32 v13, v10, v10
	v_pk_add_f32 v[6:7], v[6:7], v[26:27]
	v_pk_add_f32 v[4:5], v[4:5], v[24:25]
	v_add_f32_e32 v12, v12, v13
	v_cvt_pk_bf16_f32 v234, v8, v9
	v_mul_f32_e32 v9, v5, v5
	v_mul_f32_e32 v13, v7, v7
	v_add_f32_e32 v16, v16, v17
	v_fmac_f32_e32 v9, v4, v4
	v_fmac_f32_e32 v13, v6, v6
	s_waitcnt vmcnt(6)
	v_lshlrev_b32_e32 v28, 16, v70
	v_and_b32_e32 v29, 0xffff0000, v70
	v_lshlrev_b32_e32 v30, 16, v71
	v_and_b32_e32 v31, 0xffff0000, v71
	v_add_f32_e32 v12, v16, v12
	v_add_f32_e32 v9, v9, v13
	v_add_f32_e32 v9, v12, v9
	v_pk_add_f32 v[2:3], v[2:3], v[30:31]
	v_pk_add_f32 v[12:13], v[0:1], v[28:29]
	v_mul_f32_e32 v1, v3, v3
	v_mul_f32_e32 v0, v13, v13
	v_fmac_f32_e32 v0, v12, v12
	v_fmac_f32_e32 v1, v2, v2
	v_add_f32_e32 v0, v0, v1
	v_add_f32_e32 v0, v9, v0
	ds_bpermute_b32 v1, v184, v0
	v_cvt_pk_bf16_f32 v235, v10, v11
	s_nop 1
	v_permlane16_swap_b32 v232, v234
	v_permlane16_swap_b32 v233, v235
	v_lshl_add_u64 v[240:241], v[14:15], 0, v[242:243]
	global_store_dwordx4 v[240:241], v[232:235], off
	v_cvt_pk_bf16_f32 v236, v4, v5
	v_cvt_pk_bf16_f32 v237, v6, v7
	s_waitcnt lgkmcnt(0)
	v_add_f32_e32 v0, v0, v1
	ds_bpermute_b32 v1, v185, v0
	v_cvt_pk_bf16_f32 v238, v12, v13
	v_cvt_pk_bf16_f32 v239, v2, v3
	s_nop 1
	v_permlane16_swap_b32 v236, v238
	v_permlane16_swap_b32 v237, v239
	v_lshl_add_u64 v[240:241], v[14:15], 0, v[242:243]
	global_store_dwordx4 v[240:241], v[236:239], off offset:256
	s_and_saveexec_b64 s[40:41], s[8:9]
	s_cbranch_execz .LBB0_769
	v_lshl_add_u64 v[2:3], v[64:65], 2, s[12:13]
	s_waitcnt lgkmcnt(0)
	v_add_f32_e32 v0, v0, v1
	global_atomic_add_f32 v[2:3], v0, off
